# S5 scan split over all 256 CUs: second sequence half on CUs 128-255 after a state-only pass over the first half (bit-identical state)
# speedup vs baseline: 1.0540x; 1.0022x over previous
.LBB0_827:
	s_and_b64 vcc, exec, s[0:1]
	s_cbranch_vccz .LBB0_923
	v_readlane_b32 s0, v251, 17
	s_cmpk_gt_i32 s0, 0xff
	s_cbranch_scc1 .LBB0_923
	s_lshr_b32 s101, s0, 7
	s_lshl_b32 s101, s101, 5
	s_add_i32 s100, s101, 32
	v_readlane_b32 s0, v251, 22
	s_add_u32 s50, s0, 0x38400000
	s_movk_i32 s0, 0x400
	v_readlane_b32 s1, v251, 23
	v_cmp_gt_i32_e64 s[6:7], s0, v172
	v_readlane_b32 s0, v251, 13
	s_addc_u32 s51, s1, 0
	s_waitcnt lgkmcnt(0)
	v_lshrrev_b32_e32 v1, 4, v170
	s_andn2_b32 s0, s0, 63
	s_waitcnt vmcnt(0)
	v_bfe_u32 v110, v172, 4, 4
	v_lshlrev_b32_e32 v12, 2, v1
	s_add_i32 s0, s0, 64
	v_max_i32_e32 v39, 0x200, v172
	v_and_b32_e32 v108, 15, v172
	v_ashrrev_i32_e32 v4, 6, v172
	v_lshlrev_b32_e32 v8, 3, v110
	v_or_b32_e32 v22, s0, v12
	v_or_b32_e32 v23, 1, v12
	v_or_b32_e32 v24, 2, v12
	v_or_b32_e32 v26, 16, v12
	v_or_b32_e32 v28, 18, v12
	v_or_b32_e32 v30, 32, v12
	v_or_b32_e32 v32, 34, v12
	v_or_b32_e32 v34, 48, v12
	v_or_b32_e32 v12, 50, v12
	v_sub_u32_e32 v39, v39, v172
	v_lshlrev_b32_e32 v109, 3, v172
	v_and_b32_e32 v5, -4, v4
	v_add_u32_e32 v0, 0, v8
	v_mul_u32_u24_e32 v9, 56, v110
	v_lshlrev_b32_e32 v10, 2, v108
	v_lshlrev_b32_e32 v25, 3, v24
	v_or_b32_e32 v24, s0, v24
	v_lshlrev_b32_e32 v27, 3, v26
	v_or_b32_e32 v26, s0, v26
	v_lshlrev_b32_e32 v29, 3, v28
	v_or_b32_e32 v28, s0, v28
	v_lshlrev_b32_e32 v31, 3, v30
	v_or_b32_e32 v30, s0, v30
	v_lshlrev_b32_e32 v33, 3, v32
	v_or_b32_e32 v32, s0, v32
	v_lshlrev_b32_e32 v35, 3, v34
	v_or_b32_e32 v34, s0, v34
	v_lshlrev_b32_e32 v36, 3, v12
	v_or_b32_e32 v12, s0, v12
	v_add_u32_e32 v39, 0x1ff, v39
	s_add_i32 s0, 0, 0x10a04
	v_cmp_eq_u32_e32 vcc, 0, v5
	v_cmp_eq_u32_e64 s[8:9], v110, v108
	v_add3_u32 v111, v0, v9, v10
	v_lshrrev_b32_e32 v0, 1, v170
	v_add_u32_e32 v40, s0, v109
	s_movk_i32 s0, 0x19ff
	v_lshlrev_b32_e32 v42, 3, v39
	s_and_b64 s[56:57], vcc, s[8:9]
	v_and_b32_e32 v11, 8, v0
	v_readlane_b32 s2, v251, 26
	v_and_b32_e32 v0, 1, v172
	v_cmp_lt_u32_e32 vcc, s0, v39
	v_and_b32_e32 v42, 0xfffff000, v42
	s_brev_b32 s0, 4
	s_lshl_b32 s1, s2, 4
	v_cmp_eq_u32_e64 s[8:9], 0, v0
	v_mov_b32_e32 v0, 0x3ffffffe
	v_lshrrev_b32_e32 v41, 9, v39
	v_cmp_gt_u32_e64 s[20:21], s0, v39
	v_add_u32_e32 v39, v40, v42
	v_or_b32_e32 v13, s1, v108
	v_bitop3_b32 v0, s1, v0, v108 bitop3:0xc8
	s_movk_i32 s1, 0x440
	v_cmp_ge_u32_e64 s[22:23], v39, v40
	v_cmp_gt_i32_e64 s[10:11], s1, v172
	s_and_b64 s[0:1], s[22:23], s[20:21]
	v_or_b32_e32 v4, 3, v4
	s_and_b64 s[22:23], vcc, s[0:1]
	s_add_i32 s0, 0, 0x2000
	v_lshl_add_u32 v128, v4, 9, s0
	v_lshl_add_u32 v129, v5, 9, s0
	s_add_i32 s0, 0, 0x4000
	v_lshrrev_b32_e32 v9, 5, v170
	v_add_u32_e32 v131, s0, v8
	s_add_i32 s0, 0, 0xe800
	v_cmp_ge_i32_e64 s[12:13], s2, v9
	v_sub_u32_e32 v18, s2, v9
	v_or_b32_e32 v20, 2, v9
	v_or_b32_e32 v21, 4, v9
	v_or_b32_e32 v9, 6, v9
	v_lshl_add_u32 v132, v172, 2, s0
	v_readlane_b32 s0, v251, 24
	v_add_u32_e32 v10, 0, v10
	v_ashrrev_i32_e32 v14, 1, v13
	v_and_b32_e32 v17, 48, v172
	v_lshl_add_u32 v117, v13, 1, 0
	v_mul_u32_u24_e32 v13, 0x10c, v108
	v_cmp_ge_i32_e64 s[14:15], s2, v20
	v_sub_u32_e32 v20, s2, v20
	v_cmp_ge_i32_e64 s[16:17], s2, v21
	v_sub_u32_e32 v21, s2, v21
	v_cmp_ge_i32_e64 s[18:19], s2, v9
	v_sub_u32_e32 v9, s2, v9
	v_lshlrev_b32_e32 v96, 1, v108
	v_readlane_b32 s1, v251, 25
	s_load_dwordx2 s[52:53], s[48:49], 0x68
	s_load_dwordx2 s[54:55], s[48:49], 0x28
	s_load_dwordx8 s[24:31], s[48:49], 0x48
	v_lshlrev_b32_e32 v15, 1, v170
	v_add3_u32 v118, v10, v13, v17
	v_lshl_add_u32 v18, v18, 10, v10
	v_lshl_add_u32 v20, v20, 10, v10
	v_lshl_add_u32 v21, v21, 10, v10
	v_lshl_add_u32 v9, v9, 10, v10
	v_lshlrev_b32_e32 v10, 5, v1
	v_mul_u32_u24_e32 v124, 0x440, v1
	v_lshl_add_u64 v[98:99], s[0:1], 0, v[96:97]
	s_add_i32 s0, s2, 0x1800
	v_lshlrev_b32_e32 v1, 13, v1
	v_and_b32_e32 v15, 64, v15
	v_add_u32_e32 v134, s0, v1
	v_readlane_b32 s0, v251, 15
	v_ashrrev_i32_e32 v2, 5, v172
	v_lshl_add_u32 v37, v14, 7, 0
	v_sub_u32_e32 v14, v14, v15
	v_ashrrev_i32_e32 v15, 8, v172
	v_add_u32_e32 v173, 0x200, v172
	s_lshl_b32 s48, s0, 4
	s_add_i32 s0, s2, 0x1000
	v_and_b32_e32 v92, -2, v2
	v_lshlrev_b32_e32 v6, 9, v108
	s_add_i32 s33, 0, 0x10a00
	v_or_b32_e32 v94, 1, v2
	v_lshlrev_b32_e32 v119, 10, v5
	v_lshlrev_b32_e32 v120, 3, v15
	v_mul_i32_i24_e32 v121, 0x1100, v15
	v_ashrrev_i32_e32 v15, 8, v173
	v_add_u32_e32 v41, 1, v41
	v_add_u32_e32 v135, s0, v1
	s_add_i32 s0, s2, 0x800
	v_lshl_add_u32 v3, v170, 7, 0
	v_add_u32_e32 v7, s33, v6
	v_lshl_add_u32 v112, v0, 2, 0
	v_bfe_u32 v113, v172, 1, 3
	v_and_b32_e32 v0, 8, v109
	v_mul_u32_u24_e32 v16, 0x110, v108
	v_lshlrev_b32_e32 v13, 3, v92
	v_lshlrev_b32_e32 v2, 3, v94
	v_lshlrev_b32_e32 v19, 6, v11
	v_lshlrev_b32_e32 v22, 3, v22
	v_lshlrev_b32_e32 v24, 3, v24
	v_lshlrev_b32_e32 v26, 3, v26
	v_lshlrev_b32_e32 v28, 3, v28
	v_lshlrev_b32_e32 v30, 3, v30
	v_lshlrev_b32_e32 v32, 3, v32
	v_lshlrev_b32_e32 v34, 3, v34
	v_lshlrev_b32_e32 v12, 3, v12
	v_lshlrev_b32_e32 v11, 3, v11
	v_lshlrev_b32_e32 v14, 3, v14
	v_lshlrev_b32_e32 v122, 3, v15
	v_mul_i32_i24_e32 v123, 0x1100, v15
	v_mul_u32_u24_e32 v125, 0x110, v23
	v_or_b32_e32 v15, 0x400, v119
	v_or_b32_e32 v23, 0x800, v119
	v_lshlrev_b32_e32 v38, 10, v4
	v_and_b32_e32 v126, 0xfffffe, v41
	v_readlane_b32 s49, v251, 17
	s_and_b32 s49, s49, 0x7f
	v_add_u32_e32 v136, s0, v1
	s_add_i32 s0, 0, 0x6000
	v_cmp_lt_u32_e64 s[4:5], 63, v172
	v_mul_u32_u24_e32 v114, 0x110, v110
	v_lshlrev_b32_e32 v115, 5, v113
	v_lshlrev_b32_e32 v116, 1, v0
	v_ashrrev_i32_e32 v93, 31, v92
	v_ashrrev_i32_e32 v95, 31, v94
	v_lshl_add_u32 v127, v126, 9, v172
	v_cmp_ne_u32_e64 s[20:21], v41, v126
	v_add_u32_e32 v130, 0, v6
	v_add_u32_e32 v133, 0xfffffe00, v172
	s_lshl_b32 s35, s49, 4
	v_add_u32_e32 v137, s2, v1
	v_add3_u32 v138, v16, v17, s0
	v_add_u32_e32 v139, v3, v13
	v_add_u32_e32 v140, v3, v2
	v_add_u32_e32 v141, v111, v15
	v_add_u32_e32 v142, v111, v23
	v_add_u32_e32 v143, v111, v38
	v_add_u32_e32 v144, v7, v10
	v_add_u32_e32 v145, 0, v22
	v_add_u32_e32 v146, v7, v25
	v_add_u32_e32 v147, 0, v24
	v_add_u32_e32 v148, v7, v27
	v_add_u32_e32 v149, 0, v26
	v_add_u32_e32 v150, v7, v29
	v_add_u32_e32 v151, 0, v28
	v_add_u32_e32 v152, v7, v31
	v_add_u32_e32 v153, 0, v30
	v_add_u32_e32 v154, v7, v33
	v_add_u32_e32 v155, 0, v32
	v_add_u32_e32 v156, v7, v35
	v_add_u32_e32 v157, 0, v34
	v_add_u32_e32 v158, v7, v36
	v_add_u32_e32 v159, 0, v12
	v_add_u32_e32 v160, v37, v11
	v_add_u32_e32 v161, 0, v14
	v_lshlrev_b32_e32 v96, 1, v0
	v_add_u32_e32 v162, v18, v19
	v_add_u32_e32 v163, v20, v19
	v_add_u32_e32 v164, v21, v19
	v_add_u32_e32 v165, v9, v19
	s_branch .LBB0_831

.LBB0_917:
	s_add_i32 s36, s36, 1
	s_mov_b64 s[0:1], 0x10000
	v_lshl_add_u64 v[82:83], v[82:83], 0, s[0:1]
	v_lshl_add_u64 v[84:85], v[84:85], 0, s[0:1]
	v_lshl_add_u64 v[86:87], v[86:87], 0, s[0:1]
	s_cmp_eq_u32 s36, s100
	v_lshl_add_u64 v[88:89], v[88:89], 0, s[0:1]
	s_cbranch_scc1 .LBB0_830
.LBB0_918:
	s_waitcnt vmcnt(2)
	v_mov_b32_e32 v90, v53
	v_mov_b32_e32 v91, v54
	v_mov_b32_e32 v102, v52
	v_mov_b32_e32 v103, v55
	v_pk_add_f32 v[90:91], v[90:91], v[102:103]
	v_lshlrev_b32_e32 v102, 16, v48
	v_add_f32_e32 v90, v90, v91
	v_fmamk_f32 v90, v90, 0x3a800000, v207
	v_rsq_f32_e32 v90, v90
	v_and_b32_e32 v103, 0xffff0000, v48
	v_lshlrev_b32_e32 v104, 16, v49
	v_and_b32_e32 v105, 0xffff0000, v49
	s_bitcmp1_b32 s36, 0
	v_pk_mul_f32 v[102:103], v[90:91], v[102:103] op_sel_hi:[0,1]
	v_pk_mul_f32 v[104:105], v[90:91], v[104:105] op_sel_hi:[0,1]
	s_cselect_b32 s37, 0x4400, 0
	v_cvt_pk_bf16_f32 v102, v102, v103
	v_cvt_pk_bf16_f32 v103, v104, v105
	v_lshlrev_b32_e32 v104, 16, v50
	v_and_b32_e32 v105, 0xffff0000, v50
	v_lshlrev_b32_e32 v106, 16, v51
	v_and_b32_e32 v107, 0xffff0000, v51
	s_add_i32 s0, s37, 0
	v_pk_mul_f32 v[104:105], v[90:91], v[104:105] op_sel_hi:[0,1]
	v_pk_mul_f32 v[90:91], v[90:91], v[106:107] op_sel_hi:[0,1]
	v_cvt_pk_bf16_f32 v104, v104, v105
	v_cvt_pk_bf16_f32 v105, v90, v91
	v_add_u32_e32 v90, s0, v115
	v_add3_u32 v166, v90, v116, v114
	v_add_u32_e32 v90, v166, v121
	ds_write_b128 v90, v[102:105] offset:24576
	s_waitcnt vmcnt(0)
	v_mov_b32_e32 v90, v61
	v_mov_b32_e32 v91, v62
	v_mov_b32_e32 v102, v60
	v_mov_b32_e32 v103, v63
	v_pk_add_f32 v[90:91], v[90:91], v[102:103]
	v_lshlrev_b32_e32 v102, 16, v56
	v_add_f32_e32 v90, v90, v91
	v_fmamk_f32 v90, v90, 0x3a800000, v207
	v_rsq_f32_e32 v90, v90
	v_and_b32_e32 v103, 0xffff0000, v56
	v_lshlrev_b32_e32 v104, 16, v57
	v_and_b32_e32 v105, 0xffff0000, v57
	v_pk_mul_f32 v[102:103], v[90:91], v[102:103] op_sel_hi:[0,1]
	v_pk_mul_f32 v[104:105], v[90:91], v[104:105] op_sel_hi:[0,1]
	s_add_i32 s38, s36, 1
	s_cmp_eq_u32 s38, s100
	v_readlane_b32 s38, v251, 11
	v_cvt_pk_bf16_f32 v102, v102, v103
	v_cvt_pk_bf16_f32 v103, v104, v105
	v_lshlrev_b32_e32 v104, 16, v58
	v_and_b32_e32 v105, 0xffff0000, v58
	v_lshlrev_b32_e32 v106, 16, v59
	v_and_b32_e32 v107, 0xffff0000, v59
	s_cselect_b64 s[0:1], -1, 0
	s_lshl_b32 s2, s36, 5
	v_readlane_b32 s39, v251, 12
	v_pk_mul_f32 v[104:105], v[90:91], v[104:105] op_sel_hi:[0,1]
	v_pk_mul_f32 v[90:91], v[90:91], v[106:107] op_sel_hi:[0,1]
	s_mov_b32 s41, s39
	s_add_i32 s40, s2, 32
	v_writelane_b32 v251, s38, 11
	v_cvt_pk_bf16_f32 v104, v104, v105
	v_cvt_pk_bf16_f32 v105, v90, v91
	v_add_u32_e32 v90, v166, v123
	s_lshl_b64 s[2:3], s[40:41], 11
	v_writelane_b32 v251, s39, 12
	s_lshl_b64 s[38:39], s[40:41], 4
	ds_write_b128 v90, v[102:105] offset:24576
	v_lshl_add_u64 v[90:91], v[70:71], 0, s[2:3]
	v_lshl_add_u64 v[102:103], v[72:73], 0, s[38:39]
	v_lshl_add_u64 v[104:105], v[74:75], 0, s[2:3]
	v_lshl_add_u64 v[106:107], v[76:77], 0, s[38:39]
	v_add_u32_e32 v166, s37, v138
	s_mov_b64 s[2:3], 0
	s_mov_b32 s37, 0
	s_branch .LBB0_920
.LBB0_919:
	s_cmp_lt_u32 s36, s101
	s_cbranch_scc1 .Ls5_state_only
	ds_read_b128 v[174:177], v166
	ds_read_b128 v[178:181], v166 offset:64
	ds_read_b128 v[182:185], v166 offset:128
	ds_read_b128 v[186:189], v166 offset:192
	s_and_b32 s38, s37, 1
	s_waitcnt lgkmcnt(3)
	v_mfma_f32_16x16x32_bf16 v[64:67], v[174:177], v[20:23], v[64:67]
	s_xor_b32 s39, s38, 1
	s_mulk_i32 s39, 0x1100
	s_waitcnt lgkmcnt(1)
	v_mfma_f32_16x16x32_bf16 v[190:193], v[182:185], v[28:31], 0
	v_mfma_f32_16x16x32_bf16 v[64:67], v[178:181], v[24:27], v[64:67]
	s_waitcnt lgkmcnt(0)
	v_mfma_f32_16x16x32_bf16 v[190:193], v[186:189], v[32:35], v[190:193]
	s_nop 7
	v_pk_add_f32 v[200:201], v[64:65], v[190:191]
	v_add_u32_e32 v64, s39, v117
	v_pk_add_f32 v[198:199], v[66:67], v[192:193]
	v_cvt_pk_bf16_f32 v65, v200, s0
	v_add_u32_e32 v66, v64, v124
	ds_write_b16 v66, v65 offset:59392
	v_cvt_pk_bf16_f32 v65, v201, s0
	v_add_u32_e32 v64, v64, v125
	ds_write_b16 v64, v65 offset:59392
	v_cvt_pk_bf16_f32 v65, v198, s0
	ds_write_b16 v64, v65 offset:59664
	v_cvt_pk_bf16_f32 v65, v199, s0
	ds_write_b16 v64, v65 offset:59936
	s_mulk_i32 s38, 0x1100
	v_add_u32_e32 v167, s38, v118
	v_mfma_f32_16x16x32_bf16 v[64:67], v[174:177], v[44:47], 0
	ds_read_b128 v[174:177], v167 offset:59392
	v_and_b32_e32 v169, 64, v209
	v_add_u32_e32 v169, 64, v169
	v_mfma_f32_16x16x32_bf16 v[64:67], v[178:181], v[40:43], v[64:67]
	ds_read_b128 v[178:181], v167 offset:59456
	ds_read_b128 v[190:193], v167 offset:59520
	ds_read_b128 v[194:197], v167 offset:59584
	v_xor_b32_e32 v167, 1, v209
	v_mfma_f32_16x16x32_bf16 v[64:67], v[182:185], v[36:39], v[64:67]
	v_cmp_lt_i32_e32 vcc, v167, v169
	s_add_i32 s37, s37, 1
	v_add_u32_e32 v166, 0x1100, v166
	s_waitcnt lgkmcnt(3)
	v_mfma_f32_16x16x32_bf16 v[174:177], v[174:177], v[4:7], 0
	v_cndmask_b32_e32 v167, v209, v167, vcc
	v_lshlrev_b32_e32 v167, 2, v167
	s_waitcnt lgkmcnt(2)
	v_mfma_f32_16x16x32_bf16 v[174:177], v[178:181], v[8:11], v[174:177]
	ds_bpermute_b32 v178, v167, v200
	ds_bpermute_b32 v180, v167, v198
	ds_bpermute_b32 v181, v167, v199
	s_waitcnt lgkmcnt(4)
	v_mfma_f32_16x16x32_bf16 v[174:177], v[190:193], v[12:15], v[174:177]
	ds_bpermute_b32 v179, v167, v201
	s_waitcnt lgkmcnt(1)
	v_pk_mul_f32 v[180:181], v[80:81], v[180:181]
	v_mfma_f32_16x16x32_bf16 v[174:177], v[194:197], v[16:19], v[174:177]
	s_waitcnt lgkmcnt(0)
	v_pk_mul_f32 v[178:179], v[68:69], v[178:179]
	v_mfma_f32_16x16x32_bf16 v[64:67], v[186:189], v[0:3], v[64:67]
	s_nop 7
	v_add_f32_e32 v64, v174, v64
	v_mul_f32_e32 v167, 0x3d372713, v64
	v_mul_f32_e32 v167, v64, v167
	v_fma_f32 v167, v64, v167, v64
	v_add_f32_e32 v169, v175, v65
	v_mul_f32_e32 v65, 0xbfcc422a, v167
	v_mul_f32_e32 v167, 0x3d372713, v169
	v_mul_f32_e32 v167, v169, v167
	v_mul_f32_e32 v65, 0x3fb8aa3b, v65
	v_fma_f32 v167, v169, v167, v169
	v_exp_f32_e32 v65, v65
	v_mul_f32_e32 v167, 0xbfcc422a, v167
	v_mul_f32_e32 v167, 0x3fb8aa3b, v167
	v_exp_f32_e32 v167, v167
	v_add_f32_e32 v66, v176, v66
	v_mul_f32_e32 v175, 0x3d372713, v66
	v_add_f32_e32 v65, 1.0, v65
	v_mul_f32_e32 v175, v66, v175
	v_rcp_f32_e32 v65, v65
	v_fma_f32 v175, v66, v175, v66
	v_add_f32_e32 v167, 1.0, v167
	v_mul_f32_e32 v175, 0xbfcc422a, v175
	v_rcp_f32_e32 v167, v167
	v_mul_f32_e32 v175, 0x3fb8aa3b, v175
	v_exp_f32_e32 v175, v175
	v_mul_f32_e32 v64, v64, v65
	v_cvt_pk_bf16_f32 v174, v64, s0
	v_lshl_add_u64 v[64:65], v[88:89], 0, s[2:3]
	global_store_short v[64:65], v174, off
	v_mul_f32_e32 v64, v169, v167
	v_cvt_pk_bf16_f32 v167, v64, s0
	v_add_f32_e32 v64, 1.0, v175
	v_add_f32_e32 v67, v177, v67
	v_rcp_f32_e32 v169, v64
	v_mul_f32_e32 v64, 0x3d372713, v67
	v_mul_f32_e32 v64, v67, v64
	v_fma_f32 v64, v67, v64, v67
	v_mul_f32_e32 v64, 0xbfcc422a, v64
	v_mul_f32_e32 v64, 0x3fb8aa3b, v64
	v_exp_f32_e32 v174, v64
	v_lshl_add_u64 v[64:65], v[86:87], 0, s[2:3]
	global_store_short v[64:65], v167, off
	v_mul_f32_e32 v64, v66, v169
	v_add_f32_e32 v65, 1.0, v174
	v_rcp_f32_e32 v66, v65
	v_cvt_pk_bf16_f32 v167, v64, s0
	v_lshl_add_u64 v[64:65], v[84:85], 0, s[2:3]
	global_store_short v[64:65], v167, off
	v_mul_f32_e32 v64, v67, v66
	v_cvt_pk_bf16_f32 v66, v64, s0
	v_lshl_add_u64 v[64:65], v[82:83], 0, s[2:3]
	s_add_u32 s2, s2, 0x4000
	s_addc_u32 s3, s3, 0
	global_store_short v[64:65], v66, off
	v_pk_fma_f32 v[66:67], v[78:79], v[198:199], v[180:181]
	v_pk_fma_f32 v[64:65], v[100:101], v[200:201], v[178:179]
	s_cmp_eq_u32 s2, 0x10000
	s_cbranch_scc1 .LBB0_917

.Ls5_state_only:
	ds_read_b128 v[174:177], v166
	ds_read_b128 v[178:181], v166 offset:64
	ds_read_b128 v[182:185], v166 offset:128
	ds_read_b128 v[186:189], v166 offset:192
	s_and_b32 s38, s37, 1
	s_waitcnt lgkmcnt(3)
	v_mfma_f32_16x16x32_bf16 v[64:67], v[174:177], v[20:23], v[64:67]
	s_xor_b32 s39, s38, 1
	s_mulk_i32 s39, 0x1100
	s_waitcnt lgkmcnt(1)
	v_mfma_f32_16x16x32_bf16 v[190:193], v[182:185], v[28:31], 0
	v_mfma_f32_16x16x32_bf16 v[64:67], v[178:181], v[24:27], v[64:67]
	s_waitcnt lgkmcnt(0)
	v_mfma_f32_16x16x32_bf16 v[190:193], v[186:189], v[32:35], v[190:193]
	v_and_b32_e32 v169, 64, v209
	v_add_u32_e32 v169, 64, v169
	v_xor_b32_e32 v167, 1, v209
	v_cmp_lt_i32_e32 vcc, v167, v169
	s_add_i32 s37, s37, 1
	v_add_u32_e32 v166, 0x1100, v166
	v_cndmask_b32_e32 v167, v209, v167, vcc
	v_lshlrev_b32_e32 v167, 2, v167
	s_nop 0
	v_pk_add_f32 v[200:201], v[64:65], v[190:191]
	v_add_u32_e32 v64, s39, v117
	v_pk_add_f32 v[198:199], v[66:67], v[192:193]
	ds_bpermute_b32 v178, v167, v200
	ds_bpermute_b32 v180, v167, v198
	ds_bpermute_b32 v181, v167, v199
	ds_bpermute_b32 v179, v167, v201
	v_cvt_pk_bf16_f32 v65, v200, s0
	v_add_u32_e32 v66, v64, v124
	ds_write_b16 v66, v65 offset:59392
	v_cvt_pk_bf16_f32 v65, v201, s0
	v_add_u32_e32 v64, v64, v125
	ds_write_b16 v64, v65 offset:59392
	v_cvt_pk_bf16_f32 v65, v198, s0
	ds_write_b16 v64, v65 offset:59664
	v_cvt_pk_bf16_f32 v65, v199, s0
	ds_write_b16 v64, v65 offset:59936
	s_waitcnt lgkmcnt(4)
	v_pk_mul_f32 v[180:181], v[80:81], v[180:181]
	v_pk_mul_f32 v[178:179], v[68:69], v[178:179]
	s_add_u32 s2, s2, 0x4000
	s_addc_u32 s3, s3, 0
	v_pk_fma_f32 v[66:67], v[78:79], v[198:199], v[180:181]
	v_pk_fma_f32 v[64:65], v[100:101], v[200:201], v[178:179]
	s_cmp_eq_u32 s2, 0x10000
	s_cbranch_scc1 .LBB0_917
	s_branch .LBB0_920
